# start-up grid sync: only workgroup 0 (which zeroed the barrier words) does the L2 write-back before arriving; L1 invalidate after the sync dropped (nothing read through L1 yet, barrier words only via
# speedup vs baseline: 1.0260x; 1.0001x over previous
.LBB0_3:
	s_or_b64 exec, exec, s[4:5]
	v_cmp_gt_i32_e32 vcc, 32, v2
	s_and_saveexec_b64 s[4:5], vcc
	v_lshl_add_u32 v3, v2, 2, 0
	v_add_u32_e32 v3, 0x22000, v3
	v_mov_b32_e32 v4, 0
	ds_write_b32 v3, v4
	s_or_b64 exec, exec, s[4:5]
	v_lshrrev_b32_e32 v3, 20, v0
	v_lshrrev_b32_e32 v0, 10, v0
	v_or_b32_e32 v0, v0, v3
	s_movk_i32 s4, 0x3ff
	v_and_or_b32 v0, v0, s4, v1
	v_cmp_eq_u32_e32 vcc, 0, v0
	s_waitcnt vmcnt(0) lgkmcnt(0)
	s_barrier
	s_and_saveexec_b64 s[4:5], vcc
	s_cbranch_execz .LBB0_15
	v_readlane_b32 s6, v254, 0
	s_cmp_lg_u32 s6, 0
	s_cbranch_scc1 .Lmy_su_norel
	buffer_wbl2 sc1
	s_waitcnt vmcnt(0)
.Lmy_su_norel:
	s_load_dwordx2 s[2:3], s[2:3], 0x58
	v_mov_b32_e32 v4, 0
	s_mov_b64 s[6:7], exec
	v_mbcnt_lo_u32_b32 v3, s6, 0
	v_mbcnt_hi_u32_b32 v3, s7, v3
	s_waitcnt lgkmcnt(0)
	global_load_dword v0, v4, s[2:3] offset:40
	v_cmp_eq_u32_e32 vcc, 0, v3
	s_and_saveexec_b64 s[8:9], vcc
	s_cbranch_execz .LBB0_8
	s_bcnt1_i32_b64 s6, s[6:7]
	v_mov_b32_e32 v5, s6
	global_atomic_add v5, v4, v5, s[2:3] offset:32 sc0

.LBB0_14:
.LBB0_15:
	s_or_b64 exec, exec, s[4:5]
	s_mov_b32 s25, 0
	v_cmp_eq_u32_e32 vcc, 0, v2
	s_barrier
	s_and_saveexec_b64 s[2:3], vcc
	s_cbranch_execz .LBB0_18
	s_mov_b64 s[4:5], exec
	v_mbcnt_lo_u32_b32 v0, s4, 0
	v_mbcnt_hi_u32_b32 v0, s5, v0
	v_cmp_eq_u32_e32 vcc, 0, v0
	s_getreg_b32 s6, hwreg(HW_REG_XCC_ID, 0, 4)
	s_and_b64 s[8:9], exec, vcc
	s_mov_b64 exec, s[8:9]
	s_cbranch_execz .LBB0_18
	s_lshl_b32 s6, s6, 8
	s_and_b32 s6, s6, 0xf00
	s_add_u32 s6, s16, s6
	s_addc_u32 s7, s17, 0
	s_bcnt1_i32_b64 s4, s[4:5]
	v_mov_b32_e32 v0, 0x3780000
	v_mov_b32_e32 v2, s4
	global_atomic_add v0, v2, s[6:7] offset:1024
